# S5 mode-1 items beyond four static rounds are claimed dynamically via per-partition atomic counters (fast workgroups absorb the 256 extra items)
# speedup vs baseline: 1.0093x; 1.0093x over previous
.LBB0_637:
	v_readlane_b32 s0, v253, 0
	v_readlane_b32 s1, v253, 1
	v_readlane_b32 s2, v253, 2
	v_readlane_b32 s3, v253, 3
	v_mov_b32_e32 v0, v170
	s_mov_b64 s[0:1], s[2:3]
	s_and_b64 s[0:1], s[78:79], exec
	v_ashrrev_i32_e32 v0, 6, v0
	s_movk_i32 s0, 0x84
	s_cselect_b32 s16, 0x80, s0
	v_add_u32_e32 v1, s71, v0
	v_sub_u32_e32 v105, s75, v1
	s_lshl_b32 s17, s16, 6
	v_cmp_gt_i32_e32 vcc, s17, v105
	s_and_saveexec_b64 s[0:1], vcc
	s_cbranch_execz .LBB0_654
	v_cvt_f32_u32_e32 v1, s16
	s_movk_i32 s2, 0x4a00
	v_mul_lo_u32 v0, v0, s2
	v_readlane_b32 s2, v255, 39
	v_rcp_iflag_f32_e32 v1, v1
	s_lshl_b32 s18, s2, 6
	s_lshl_b32 s19, s2, 9
	s_sub_i32 s2, 0, s16
	v_mul_f32_e32 v1, 0x4f7ffffe, v1
	v_cvt_u32_f32_e32 v1, v1
	v_add_u32_e32 v194, 0, v0
	s_mov_b64 s[6:7], 0
	v_mul_lo_u32 v0, s2, v1
	v_mul_hi_u32 v0, v1, v0
	v_add_u32_e32 v195, v1, v0
	v_readlane_b32 s24, v253, 2
	v_readlane_b32 s25, v253, 3
	v_readlane_b32 s28, v255, 39
	s_lshr_b32 s29, s71, 3
	s_and_b32 s29, s29, 7
	s_lshl_b32 s28, s28, 3
	s_add_i32 s28, s28, s29
	s_lshr_b32 s26, s28, 1
	s_lshl_b32 s26, s26, 8
	s_and_b32 s27, s28, 1
	s_lshl_b32 s27, s27, 7
	s_add_i32 s26, s26, s27
	s_add_i32 s26, s26, 0xc0040
	s_add_u32 s24, s24, s26
	s_addc_u32 s25, s25, 0
	s_branch .LBB0_640
.LBB0_639:
	s_or_b64 exec, exec, s[2:3]
	v_readfirstlane_b32 s28, v105
	s_add_i32 s28, s28, s72
	s_cmp_lt_u32 s28, 0x2000
	s_cbranch_scc1 .Ls5c_next
	s_cmp_le_u32 s17, 0x2000
	s_cbranch_scc1 .LBB0_654
	s_mov_b64 s[26:27], exec
	s_mov_b64 exec, 1
	v_mov_b32_e32 v184, 1
	v_mov_b32_e32 v185, 0
	global_atomic_add v184, v185, v184, s[24:25] sc0
	s_waitcnt vmcnt(0)
	v_readfirstlane_b32 s28, v184
	s_mov_b64 exec, s[26:27]
	s_lshl_b32 s28, s28, 3
	s_add_i32 s28, s28, s29
	s_add_i32 s28, s28, 0x2000
	s_cmp_ge_u32 s28, s17
	s_cbranch_scc1 .LBB0_654
.Ls5c_next:
	v_mov_b32_e32 v105, s28
